# attention: per-unit dispatch to a straight-line copy of the steady loop without row-max/rescale code (one taken branch per iteration instead of eight)
# speedup vs baseline: 1.0156x; 1.0104x over previous
.LBB0_483:
	s_lshl_b32 s2, s5, 1
	s_ashr_i32 s3, s4, 2
	s_add_i32 s5, s2, s3
	s_lshl_b64 s[2:3], s[88:89], 10
	s_add_u32 s8, s86, s2
	s_addc_u32 s9, s87, s3
	s_lshl_b32 s2, s4, 6
	s_ashr_i32 s3, s2, 31
	s_lshl_b64 s[6:7], s[2:3], 1
	s_add_u32 s8, s8, s6
	s_addc_u32 s9, s9, s7
	s_mul_hi_i32 s2, s5, 0x108000
	s_mul_i32 s5, s5, 0x108000
	s_add_u32 s14, s40, s5
	s_addc_u32 s15, s72, s2
	v_mov_b32_e32 v42, v234
	s_add_u32 s16, s73, s5
	s_addc_u32 s17, s74, s2
	v_readfirstlane_b32 s10, v42
	s_ashr_i32 s2, s10, 6
	s_ashr_i32 s3, s2, 31
	s_lshl_b64 s[4:5], s[2:3], 15
	s_add_u32 s8, s8, s4
	s_addc_u32 s9, s9, s5
	s_and_b32 s5, s10, 0x3fffffc0
	s_lshl_b32 s10, s2, 9
	s_ashr_i32 s11, s10, 31
	s_lshl_b64 s[10:11], s[10:11], 1
	s_add_u32 s14, s14, s10
	s_addc_u32 s15, s15, s11
	s_add_u32 s10, s16, s10
	s_addc_u32 s11, s17, s11
	s_lshl_b32 s46, s2, 10
	v_and_b32_e32 v194, 63, v42
	s_cmp_lg_u32 0, -1
	v_lshlrev_b32_e32 v0, 4, v194
	s_cselect_b32 s4, 0, 0
	v_and_b32_e32 v195, 31, v42
	v_lshl_add_u64 v[182:183], s[14:15], 0, v[0:1]
	s_add_i32 s46, s46, s4
	s_mov_b32 s4, m0
	s_mov_b32 m0, s46
	s_nop 0
	global_load_lds_dwordx4 v[182:183], off
	s_mov_b32 m0, s4
	v_bfe_u32 v196, v42, 5, 1
	v_lshl_add_u64 v[82:83], s[10:11], 0, v[0:1]
	s_add_i32 s47, s46, 0x6000
	s_mov_b32 s4, m0
	s_mov_b32 m0, s47
	s_nop 0
	global_load_lds_dwordx4 v[82:83], off
	s_mov_b32 m0, s4
	v_lshlrev_b32_e32 v0, 10, v195
	v_lshl_add_u64 v[2:3], v[182:183], 0, s[38:39]
	s_add_i32 s4, s46, 0x2000
	s_mov_b32 s10, m0
	s_mov_b32 m0, s4
	s_nop 0
	global_load_lds_dwordx4 v[2:3], off
	s_mov_b32 m0, s10
	v_lshl_or_b32 v0, v196, 4, v0
	global_load_dwordx4 v[142:145], v0, s[8:9]
	global_load_dwordx4 v[134:137], v0, s[8:9] offset:32
	global_load_dwordx4 v[126:129], v0, s[8:9] offset:64
	global_load_dwordx4 v[118:121], v0, s[8:9] offset:96
	v_mov_b32_e32 v2, v1
	v_mov_b32_e32 v3, v1
	v_mov_b32_e32 v4, v1
	v_mov_b32_e32 v5, v1
	v_mov_b32_e32 v6, v1
	v_mov_b32_e32 v7, v1
	v_mov_b32_e32 v8, v1
	v_mov_b32_e32 v9, v1
	v_mov_b32_e32 v10, v1
	v_mov_b32_e32 v11, v1
	v_mov_b32_e32 v12, v1
	v_mov_b32_e32 v13, v1
	v_mov_b32_e32 v14, v1
	v_mov_b32_e32 v15, v1
	v_lshlrev_b32_e32 v0, 10, v196
	v_lshlrev_b32_e32 v16, 4, v195
	v_add3_u32 v202, 0, v0, v16
	v_mov_b32_e32 v0, v1
	v_mov_b64_e32 v[16:17], v[14:15]
	v_mov_b64_e32 v[14:15], v[12:13]
	v_mov_b64_e32 v[12:13], v[10:11]
	v_mov_b64_e32 v[10:11], v[8:9]
	v_mov_b64_e32 v[8:9], v[6:7]
	v_mov_b64_e32 v[6:7], v[4:5]
	v_mov_b64_e32 v[4:5], v[2:3]
	v_mov_b64_e32 v[2:3], v[0:1]
	v_lshl_add_u64 v[18:19], v[182:183], 0, s[42:43]
	s_add_i32 s4, s46, 0x4000
	s_mov_b32 s8, m0
	s_mov_b32 m0, s4
	s_nop 0
	global_load_lds_dwordx4 v[18:19], off
	s_mov_b32 m0, s8
	s_waitcnt vmcnt(3) lgkmcnt(0)
	s_barrier
	ds_read_b128 v[34:37], v202
	ds_read_b128 v[38:41], v202 offset:512
	v_lshlrev_b32_e32 v43, 1, v42
	v_lshlrev_b32_e32 v0, 3, v42
	v_and_b32_e32 v198, 32, v43
	s_lshl_b32 s5, s5, 2
	s_add_i32 s18, s5, 0
	v_lshl_add_u64 v[184:185], v[82:83], 0, s[38:39]
	v_and_b32_e32 v199, 24, v0
	v_add_u32_e32 v84, 0, v198
	s_mov_b32 s4, 1
	s_mov_b32 s14, 0
	s_movk_i32 s50, 0x2000
	s_movk_i32 s25, 0x4000
	s_andn2_b64 vcc, exec, s[0:1]
	v_cmp_gt_u32_e64 s[0:1], 32, v194
	v_lshlrev_b32_e32 v204, 4, v196
	v_lshl_add_u32 v200, v195, 2, s18
	s_waitcnt vmcnt(3) lgkmcnt(1)
	v_mfma_f32_32x32x16_bf16 v[18:33], v[34:37], v[142:145], v[2:17]
	s_waitcnt lgkmcnt(0)
	v_mfma_f32_32x32x16_bf16 v[2:17], v[38:41], v[142:145], v[2:17]
	ds_read_b128 v[34:37], v202 offset:2048
	ds_read_b128 v[38:41], v202 offset:2560
	s_waitcnt vmcnt(2) lgkmcnt(1)
	v_mfma_f32_32x32x16_bf16 v[18:33], v[34:37], v[134:137], v[18:33]
	s_waitcnt lgkmcnt(0)
	v_mfma_f32_32x32x16_bf16 v[2:17], v[38:41], v[134:137], v[2:17]
	ds_read_b128 v[34:37], v202 offset:4096
	ds_read_b128 v[38:41], v202 offset:4608
	s_waitcnt vmcnt(1) lgkmcnt(1)
	v_mfma_f32_32x32x16_bf16 v[18:33], v[34:37], v[126:129], v[18:33]
	ds_read_b128 v[34:37], v202 offset:6144
	s_waitcnt lgkmcnt(1)
	v_mfma_f32_32x32x16_bf16 v[2:17], v[38:41], v[126:129], v[2:17]
	ds_read_b128 v[38:41], v202 offset:6656
	s_waitcnt vmcnt(0) lgkmcnt(1)
	v_mfma_f32_32x32x16_bf16 v[18:33], v[34:37], v[118:121], v[18:33]
	v_lshlrev_b32_e32 v34, 4, v42
	v_and_b32_e32 v34, 0xc0, v34
	v_lshl_or_b32 v197, v196, 8, v34
	v_add3_u32 v203, v84, v199, v197
	s_waitcnt lgkmcnt(0)
	v_mfma_f32_32x32x16_bf16 v[2:17], v[38:41], v[118:121], v[2:17]
	s_nop 15
	s_nop 7
	s_nop 0
	v_max3_f32 v34, v18, v19, v2
	v_max3_f32 v35, v20, v21, v3
	s_nop 0
	v_max3_f32 v34, v34, v4, v5
	v_max3_f32 v35, v35, v24, v25
	s_nop 0
	v_max3_f32 v34, v34, v22, v23
	v_max3_f32 v35, v35, v8, v9
	s_nop 0
	v_max3_f32 v34, v34, v6, v7
	v_max3_f32 v35, v35, v28, v29
	s_nop 0
	v_max3_f32 v34, v34, v26, v27
	v_max3_f32 v35, v35, v12, v13
	s_nop 0
	v_max3_f32 v34, v34, v10, v11
	v_max3_f32 v35, v35, v32, v33
	s_nop 0
	v_max3_f32 v34, v34, v30, v31
	v_max3_f32 v35, v35, v16, v17
	s_nop 0
	v_max3_f32 v34, v34, v14, v15
	s_nop 0
	v_max_f32_e32 v34, v34, v35
	s_nop 0
	v_mov_b32_e32 v35, v34
	s_nop 1
	v_permlane32_swap_b32_e32 v34, v35
	v_max_f32_e32 v34, v34, v35
	s_nop 0
	v_add_f32_e32 v201, v1, v34
	v_sub_f32_e32 v18, v18, v34
	v_sub_f32_e32 v2, v2, v34
	v_sub_f32_e32 v19, v19, v34
	v_sub_f32_e32 v3, v3, v34
	v_sub_f32_e32 v20, v20, v34
	v_sub_f32_e32 v4, v4, v34
	v_sub_f32_e32 v21, v21, v34
	v_sub_f32_e32 v5, v5, v34
	v_sub_f32_e32 v22, v22, v34
	v_sub_f32_e32 v6, v6, v34
	v_sub_f32_e32 v23, v23, v34
	v_sub_f32_e32 v7, v7, v34
	v_sub_f32_e32 v24, v24, v34
	v_sub_f32_e32 v8, v8, v34
	v_sub_f32_e32 v25, v25, v34
	v_sub_f32_e32 v9, v9, v34
	v_sub_f32_e32 v26, v26, v34
	v_sub_f32_e32 v10, v10, v34
	v_sub_f32_e32 v27, v27, v34
	v_sub_f32_e32 v11, v11, v34
	v_sub_f32_e32 v28, v28, v34
	v_sub_f32_e32 v12, v12, v34
	v_sub_f32_e32 v29, v29, v34
	v_sub_f32_e32 v13, v13, v34
	v_sub_f32_e32 v30, v30, v34
	v_sub_f32_e32 v14, v14, v34
	v_sub_f32_e32 v31, v31, v34
	v_sub_f32_e32 v15, v15, v34
	v_sub_f32_e32 v32, v32, v34
	v_sub_f32_e32 v16, v16, v34
	v_sub_f32_e32 v33, v33, v34
	v_sub_f32_e32 v17, v17, v34
	s_nop 0
	v_xor_b32_e32 v34, 0x80000000, v201
	v_mov_b32_e32 v35, v34
	v_mov_b32_e32 v36, v34
	v_mov_b32_e32 v37, v34
	v_mov_b32_e32 v38, v34
	v_mov_b32_e32 v39, v34
	v_mov_b32_e32 v40, v34
	v_mov_b32_e32 v41, v34
	v_mov_b32_e32 v42, v34
	v_mov_b32_e32 v43, v34
	v_mov_b32_e32 v44, v34
	v_mov_b32_e32 v45, v34
	v_mov_b32_e32 v46, v34
	v_mov_b32_e32 v47, v34
	v_mov_b32_e32 v48, v34
	v_mov_b32_e32 v49, v34
	s_waitcnt vmcnt(0) lgkmcnt(0)
	s_barrier
	v_exp_f32_e32 v50, v2
	v_exp_f32_e32 v51, v3
	v_lshl_add_u64 v[2:3], v[182:183], 0, s[78:79]
	s_mov_b32 s5, m0
	s_mov_b32 m0, s46
	s_nop 0
	global_load_lds_dwordx4 v[2:3], off
	s_mov_b32 m0, s5
	s_add_i32 s5, s46, 0x8000
	s_mov_b32 s8, m0
	s_mov_b32 m0, s5
	s_nop 0
	global_load_lds_dwordx4 v[184:185], off
	s_mov_b32 m0, s8
	ds_read_b128 v[174:177], v202 offset:8192
	ds_read_b128 v[170:173], v202 offset:8704
	ds_read_b128 v[166:169], v202 offset:10240
	ds_read_b128 v[162:165], v202 offset:10752
	ds_read_b128 v[158:161], v202 offset:12288
	ds_read_b128 v[154:157], v202 offset:12800
	ds_read_b128 v[150:153], v202 offset:14336
	ds_read_b128 v[146:149], v202 offset:14848
	v_exp_f32_e32 v66, v18
	v_exp_f32_e32 v67, v19
	v_exp_f32_e32 v68, v20
	v_exp_f32_e32 v69, v21
	v_exp_f32_e32 v70, v22
	v_exp_f32_e32 v71, v23
	v_exp_f32_e32 v72, v24
	v_exp_f32_e32 v73, v25
	v_exp_f32_e32 v74, v26
	v_exp_f32_e32 v75, v27
	v_exp_f32_e32 v76, v28
	v_exp_f32_e32 v77, v29
	v_exp_f32_e32 v78, v30
	v_exp_f32_e32 v79, v31
	v_exp_f32_e32 v80, v32
	v_exp_f32_e32 v81, v33
	v_exp_f32_e32 v52, v4
	v_exp_f32_e32 v53, v5
	v_exp_f32_e32 v54, v6
	v_exp_f32_e32 v55, v7
	v_exp_f32_e32 v56, v8
	v_exp_f32_e32 v57, v9
	v_exp_f32_e32 v58, v10
	v_exp_f32_e32 v59, v11
	v_exp_f32_e32 v60, v12
	v_exp_f32_e32 v61, v13
	v_exp_f32_e32 v62, v14
	v_exp_f32_e32 v63, v15
	v_exp_f32_e32 v64, v16
	v_exp_f32_e32 v65, v17
	s_waitcnt vmcnt(2) lgkmcnt(0)
	s_barrier
	s_cbranch_vccnz .LBB0_499
	s_mov_b64 s[4:5], 0xa000
	v_mov_b32_e32 v205, 0
	v_readfirstlane_b32 s100, v182
	v_readfirstlane_b32 s101, v183
	v_sub_u32_e32 v186, v82, v182
	s_nop 3
	v_subrev_u32_e32 v188, s100, v182
	s_add_u32 s100, s100, 0x8000
	s_addc_u32 s101, s101, 0
	v_add_u32_e32 v186, v186, v188
	v_add_u32_e32 v187, 0xffffe000, v186
	v_add_u32_e32 v186, 0xffffc000, v186
	v_add_u32_e32 v189, 0x2000, v188
	s_movk_i32 s14, 0x4000
	s_movk_i32 s11, 0x2000
	s_mov_b32 s4, 0
	s_mov_b32 s10, 6
	v_mov_b32_e32 v18, 0
	v_mov_b32_e32 v19, v205
	v_mov_b32_e32 v20, v205
	v_mov_b32_e32 v21, v205
	v_mov_b32_e32 v22, v205
	v_mov_b32_e32 v23, v205
	v_mov_b32_e32 v24, v205
	v_mov_b32_e32 v25, v205
	v_mov_b32_e32 v26, v205
	v_mov_b32_e32 v27, v205
	v_mov_b32_e32 v28, v205
	v_mov_b32_e32 v29, v205
	v_mov_b32_e32 v30, v205
	v_mov_b32_e32 v31, v205
	v_mov_b32_e32 v32, v205
	v_mov_b32_e32 v33, v205
	v_mov_b32_e32 v2, v205
	v_mov_b32_e32 v3, v205
	v_mov_b32_e32 v4, v205
	v_mov_b32_e32 v5, v205
	v_mov_b32_e32 v6, v205
	v_mov_b32_e32 v7, v205
	v_mov_b32_e32 v8, v205
	v_mov_b32_e32 v9, v205
	v_mov_b32_e32 v10, v205
	v_mov_b32_e32 v11, v205
	v_mov_b32_e32 v12, v205
	v_mov_b32_e32 v13, v205
	v_mov_b32_e32 v14, v205
	v_mov_b32_e32 v15, v205
	v_mov_b32_e32 v16, v205
	v_mov_b32_e32 v17, v205
	s_cmp_lg_u32 s99, 0
	s_cbranch_scc1 .Lfast_485
.LBB0_485:
	v_add_u32_e32 v190, s4, v203
	ds_read_b64_tr_b16 v[178:179], v190 offset:24576
	ds_read_b64_tr_b16 v[180:181], v190 offset:25088
	s_waitcnt lgkmcnt(9)
	v_mfma_f32_32x32x16_bf16 v[98:113], v[174:177], v[142:145], v[34:49]
	v_add_f32_e32 v82, v66, v67
	v_add_f32_e32 v82, v68, v82
	v_add_f32_e32 v82, v69, v82
	v_add_f32_e32 v82, v70, v82
	v_add_f32_e32 v82, v71, v82
	v_cvt_pk_bf16_f32 v138, v66, v67
	v_cvt_pk_bf16_f32 v139, v68, v69
	ds_read_b64_tr_b16 v[174:175], v190 offset:28672
	ds_read_b64_tr_b16 v[176:177], v190 offset:29184
	v_add_f32_e32 v66, v72, v82
	s_waitcnt lgkmcnt(10)
	v_mfma_f32_32x32x16_bf16 v[82:97], v[170:173], v[142:145], v[34:49]
	v_add_f32_e32 v66, v73, v66
	v_add_f32_e32 v66, v74, v66
	v_add_f32_e32 v114, v75, v66
	v_cvt_pk_bf16_f32 v140, v70, v71
	v_cvt_pk_bf16_f32 v141, v72, v73
	ds_read_b64_tr_b16 v[66:67], v190 offset:25600
	ds_read_b64_tr_b16 v[68:69], v190 offset:26112
	s_waitcnt lgkmcnt(11)
	v_mfma_f32_32x32x16_bf16 v[98:113], v[166:169], v[134:137], v[98:113]
	v_add_f32_e32 v70, v76, v114
	v_add_f32_e32 v70, v77, v70
	v_add_f32_e32 v70, v78, v70
	v_add_f32_e32 v114, v79, v70
	v_cvt_pk_bf16_f32 v130, v74, v75
	v_cvt_pk_bf16_f32 v131, v76, v77
	ds_read_b64_tr_b16 v[70:71], v190 offset:29696
	ds_read_b64_tr_b16 v[72:73], v190 offset:30208
	s_waitcnt lgkmcnt(12)
	v_mfma_f32_32x32x16_bf16 v[82:97], v[162:165], v[134:137], v[82:97]
	v_add_f32_e32 v74, v80, v114
	v_add_f32_e32 v74, v81, v74
	v_add_f32_e32 v74, v50, v74
	v_add_f32_e32 v114, v51, v74
	v_cvt_pk_bf16_f32 v132, v78, v79
	v_cvt_pk_bf16_f32 v133, v80, v81
	ds_read_b64_tr_b16 v[74:75], v190 offset:26624
	ds_read_b64_tr_b16 v[76:77], v190 offset:27136
	s_waitcnt lgkmcnt(13)
	v_mfma_f32_32x32x16_bf16 v[98:113], v[158:161], v[126:129], v[98:113]
	v_add_f32_e32 v78, v52, v114
	v_add_f32_e32 v78, v53, v78
	v_add_f32_e32 v78, v54, v78
	v_add_f32_e32 v78, v55, v78
	v_cvt_pk_bf16_f32 v122, v50, v51
	v_cvt_pk_bf16_f32 v123, v52, v53
	ds_read_b64_tr_b16 v[50:51], v190 offset:30720
	ds_read_b64_tr_b16 v[52:53], v190 offset:31232
	s_waitcnt lgkmcnt(14)
	v_mfma_f32_32x32x16_bf16 v[82:97], v[154:157], v[126:129], v[82:97]
	v_add_f32_e32 v78, v56, v78
	v_add_f32_e32 v78, v57, v78
	v_add_f32_e32 v78, v58, v78
	v_add_f32_e32 v78, v59, v78
	v_cvt_pk_bf16_f32 v124, v54, v55
	v_cvt_pk_bf16_f32 v125, v56, v57
	ds_read_b64_tr_b16 v[54:55], v190 offset:27648
	ds_read_b64_tr_b16 v[56:57], v190 offset:28160
	s_waitcnt lgkmcnt(14)
	v_mfma_f32_32x32x16_bf16 v[98:113], v[150:153], v[118:121], v[98:113]
	v_add_f32_e32 v78, v60, v78
	v_add_f32_e32 v78, v61, v78
	v_add_f32_e32 v78, v62, v78
	v_add_f32_e32 v78, v63, v78
	v_cvt_pk_bf16_f32 v114, v58, v59
	v_cvt_pk_bf16_f32 v115, v60, v61
	ds_read_b64_tr_b16 v[58:59], v190 offset:31744
	ds_read_b64_tr_b16 v[60:61], v190 offset:32256
	v_mfma_f32_32x32x16_bf16 v[82:97], v[146:149], v[118:121], v[82:97]
	v_add_f32_e32 v78, v64, v78
	v_add_f32_e32 v78, v65, v78
	v_cvt_pk_bf16_f32 v116, v62, v63
	v_cvt_pk_bf16_f32 v117, v64, v65
	s_add_i32 s4, s11, s46
	s_mov_b32 s5, m0
	s_mov_b32 m0, s4
	s_nop 0
	global_load_lds_dwordx4 v188, s[100:101]
	s_mov_b32 m0, s5
	s_add_i32 s4, s14, s47
	s_mov_b32 s5, m0
	s_mov_b32 m0, s4
	s_nop 0
	global_load_lds_dwordx4 v186, s[100:101]
	s_mov_b32 m0, s5
	v_max_f32_e32 v62, v99, v99
	v_max_f32_e32 v63, v98, v98
	v_max_f32_e32 v62, v63, v62
	v_max3_f32 v63, v100, v101, v83
	v_max3_f32 v62, v62, v82, v84
	v_max3_f32 v62, v62, v85, v102
	v_max3_f32 v63, v63, v104, v105
	v_max3_f32 v62, v62, v103, v86
	v_max3_f32 v63, v63, v88, v89
	v_max3_f32 v62, v62, v87, v106
	v_max3_f32 v63, v63, v108, v109
	v_max3_f32 v62, v62, v107, v90
	v_max3_f32 v63, v63, v92, v93
	v_max3_f32 v62, v62, v91, v110
	v_max3_f32 v63, v63, v112, v113
	v_max3_f32 v62, v62, v111, v94
	v_max3_f32 v63, v63, v96, v97
	v_max3_f32 v62, v62, v95, v63
	v_mov_b32_e32 v63, v62
	s_nop 1
	v_permlane32_swap_b32_e32 v62, v63
	v_max_f32_e32 v63, v63, v63
	v_max_f32_e32 v62, v62, v62
	v_max_f32_e32 v62, v62, v63
	v_cmp_lt_f32_e32 vcc, s93, v62
	s_cmp_lg_u64 vcc, 0
	v_add_f32_e32 v190, v205, v78
	s_cselect_b64 s[4:5], -1, 0
	s_cbranch_vccnz .LBB0_493

.LBB0_488:
	s_add_i32 s4, s14, 0x2000
	s_cmpk_lg_i32 s14, 0x4000
	s_cselect_b32 s50, s4, 0
	v_add_u32_e32 v192, s11, v203
	ds_read_b64_tr_b16 v[150:151], v192 offset:24576
	ds_read_b64_tr_b16 v[152:153], v192 offset:25088
	s_waitcnt lgkmcnt(9)
	v_mfma_f32_32x32x16_bf16 v[66:81], v[62:65], v[142:145], v[34:49]
	v_add_f32_e32 v50, v98, v99
	v_add_f32_e32 v50, v100, v50
	v_add_f32_e32 v50, v101, v50
	v_add_f32_e32 v50, v102, v50
	v_add_f32_e32 v50, v103, v50
	v_cvt_pk_bf16_f32 v138, v98, v99
	v_cvt_pk_bf16_f32 v139, v100, v101
	ds_read_b64_tr_b16 v[146:147], v192 offset:28672
	ds_read_b64_tr_b16 v[148:149], v192 offset:29184
	v_add_f32_e32 v50, v104, v50
	v_add_f32_e32 v50, v105, v50
	v_add_f32_e32 v50, v106, v50
	v_add_f32_e32 v114, v107, v50
	s_waitcnt lgkmcnt(10)
	v_mfma_f32_32x32x16_bf16 v[50:65], v[174:177], v[142:145], v[34:49]
	v_cvt_pk_bf16_f32 v140, v102, v103
	v_cvt_pk_bf16_f32 v141, v104, v105
	ds_read_b64_tr_b16 v[98:99], v192 offset:25600
	ds_read_b64_tr_b16 v[100:101], v192 offset:26112
	s_waitcnt lgkmcnt(11)
	v_mfma_f32_32x32x16_bf16 v[66:81], v[178:181], v[134:137], v[66:81]
	v_add_f32_e32 v102, v108, v114
	v_add_f32_e32 v102, v109, v102
	v_add_f32_e32 v102, v110, v102
	v_add_f32_e32 v114, v111, v102
	v_cvt_pk_bf16_f32 v130, v106, v107
	v_cvt_pk_bf16_f32 v131, v108, v109
	ds_read_b64_tr_b16 v[102:103], v192 offset:29696
	ds_read_b64_tr_b16 v[104:105], v192 offset:30208
	s_waitcnt lgkmcnt(12)
	v_mfma_f32_32x32x16_bf16 v[50:65], v[170:173], v[134:137], v[50:65]
	v_add_f32_e32 v106, v112, v114
	v_add_f32_e32 v106, v113, v106
	v_add_f32_e32 v106, v82, v106
	v_add_f32_e32 v114, v83, v106
	v_cvt_pk_bf16_f32 v132, v110, v111
	v_cvt_pk_bf16_f32 v133, v112, v113
	ds_read_b64_tr_b16 v[106:107], v192 offset:26624
	ds_read_b64_tr_b16 v[108:109], v192 offset:27136
	s_waitcnt lgkmcnt(13)
	v_mfma_f32_32x32x16_bf16 v[66:81], v[166:169], v[126:129], v[66:81]
	v_add_f32_e32 v110, v84, v114
	v_add_f32_e32 v110, v85, v110
	v_add_f32_e32 v110, v86, v110
	v_add_f32_e32 v110, v87, v110
	v_cvt_pk_bf16_f32 v122, v82, v83
	v_cvt_pk_bf16_f32 v123, v84, v85
	ds_read_b64_tr_b16 v[82:83], v192 offset:30720
	ds_read_b64_tr_b16 v[84:85], v192 offset:31232
	s_waitcnt lgkmcnt(14)
	v_mfma_f32_32x32x16_bf16 v[50:65], v[162:165], v[126:129], v[50:65]
	v_add_f32_e32 v110, v88, v110
	v_add_f32_e32 v110, v89, v110
	v_add_f32_e32 v110, v90, v110
	v_add_f32_e32 v110, v91, v110
	v_cvt_pk_bf16_f32 v124, v86, v87
	v_cvt_pk_bf16_f32 v125, v88, v89
	ds_read_b64_tr_b16 v[86:87], v192 offset:27648
	ds_read_b64_tr_b16 v[88:89], v192 offset:28160
	s_waitcnt lgkmcnt(14)
	v_mfma_f32_32x32x16_bf16 v[66:81], v[158:161], v[118:121], v[66:81]
	v_add_f32_e32 v110, v92, v110
	v_add_f32_e32 v110, v93, v110
	v_add_f32_e32 v110, v94, v110
	v_add_f32_e32 v110, v95, v110
	v_cvt_pk_bf16_f32 v114, v90, v91
	v_cvt_pk_bf16_f32 v115, v92, v93
	ds_read_b64_tr_b16 v[90:91], v192 offset:31744
	ds_read_b64_tr_b16 v[92:93], v192 offset:32256
	v_mfma_f32_32x32x16_bf16 v[50:65], v[154:157], v[118:121], v[50:65]
	v_add_f32_e32 v110, v96, v110
	v_add_f32_e32 v110, v97, v110
	v_cvt_pk_bf16_f32 v116, v94, v95
	v_cvt_pk_bf16_f32 v117, v96, v97
	v_max_f32_e32 v94, v67, v67
	v_max_f32_e32 v95, v66, v66
	v_max_f32_e32 v94, v95, v94
	s_nop 3
	v_max3_f32 v95, v68, v69, v51
	v_max3_f32 v94, v94, v50, v52
	v_max3_f32 v94, v94, v53, v70
	v_max3_f32 v95, v95, v72, v73
	v_max3_f32 v94, v94, v71, v54
	v_max3_f32 v95, v95, v56, v57
	v_max3_f32 v94, v94, v55, v74
	v_max3_f32 v95, v95, v76, v77
	v_max3_f32 v94, v94, v75, v58
	v_max3_f32 v95, v95, v60, v61
	v_max3_f32 v94, v94, v59, v78
	v_max3_f32 v95, v95, v80, v81
	v_max3_f32 v94, v94, v79, v62
	v_max3_f32 v95, v95, v64, v65
	v_max3_f32 v94, v94, v63, v95
	v_mov_b32_e32 v95, v94
	s_nop 1
	v_permlane32_swap_b32_e32 v94, v95
	v_max_f32_e32 v95, v95, v95
	v_max_f32_e32 v94, v94, v94
	s_add_i32 s4, s14, s46
	s_mov_b32 s5, m0
	s_mov_b32 m0, s4
	s_nop 0
	global_load_lds_dwordx4 v189, s[100:101]
	s_mov_b32 m0, s5
	v_max_f32_e32 v94, v94, v95
	s_add_i32 s4, s50, s47
	s_mov_b32 s5, m0
	s_mov_b32 m0, s4
	s_nop 0
	global_load_lds_dwordx4 v187, s[100:101]
	s_mov_b32 m0, s5
	v_cmp_lt_f32_e32 vcc, s93, v94
	s_cmp_lg_u64 vcc, 0
	v_add_f32_e32 v205, v190, v110
	s_cselect_b64 s[4:5], -1, 0
	s_cbranch_vccnz .LBB0_496

.Lfast_485:
	v_add_u32_e32 v190, s4, v203
	ds_read_b64_tr_b16 v[178:179], v190 offset:24576
	ds_read_b64_tr_b16 v[180:181], v190 offset:25088
	s_waitcnt lgkmcnt(9)
	v_mfma_f32_32x32x16_bf16 v[98:113], v[174:177], v[142:145], v[34:49]
	v_add_f32_e32 v82, v66, v67
	v_add_f32_e32 v82, v68, v82
	v_add_f32_e32 v82, v69, v82
	v_add_f32_e32 v82, v70, v82
	v_add_f32_e32 v82, v71, v82
	v_cvt_pk_bf16_f32 v138, v66, v67
	v_cvt_pk_bf16_f32 v139, v68, v69
	ds_read_b64_tr_b16 v[174:175], v190 offset:28672
	ds_read_b64_tr_b16 v[176:177], v190 offset:29184
	v_add_f32_e32 v66, v72, v82
	s_waitcnt lgkmcnt(10)
	v_mfma_f32_32x32x16_bf16 v[82:97], v[170:173], v[142:145], v[34:49]
	v_add_f32_e32 v66, v73, v66
	v_add_f32_e32 v66, v74, v66
	v_add_f32_e32 v114, v75, v66
	v_cvt_pk_bf16_f32 v140, v70, v71
	v_cvt_pk_bf16_f32 v141, v72, v73
	ds_read_b64_tr_b16 v[66:67], v190 offset:25600
	ds_read_b64_tr_b16 v[68:69], v190 offset:26112
	s_waitcnt lgkmcnt(11)
	v_mfma_f32_32x32x16_bf16 v[98:113], v[166:169], v[134:137], v[98:113]
	v_add_f32_e32 v70, v76, v114
	v_add_f32_e32 v70, v77, v70
	v_add_f32_e32 v70, v78, v70
	v_add_f32_e32 v114, v79, v70
	v_cvt_pk_bf16_f32 v130, v74, v75
	v_cvt_pk_bf16_f32 v131, v76, v77
	ds_read_b64_tr_b16 v[70:71], v190 offset:29696
	ds_read_b64_tr_b16 v[72:73], v190 offset:30208
	s_waitcnt lgkmcnt(12)
	v_mfma_f32_32x32x16_bf16 v[82:97], v[162:165], v[134:137], v[82:97]
	v_add_f32_e32 v74, v80, v114
	v_add_f32_e32 v74, v81, v74
	v_add_f32_e32 v74, v50, v74
	v_add_f32_e32 v114, v51, v74
	v_cvt_pk_bf16_f32 v132, v78, v79
	v_cvt_pk_bf16_f32 v133, v80, v81
	ds_read_b64_tr_b16 v[74:75], v190 offset:26624
	ds_read_b64_tr_b16 v[76:77], v190 offset:27136
	s_waitcnt lgkmcnt(13)
	v_mfma_f32_32x32x16_bf16 v[98:113], v[158:161], v[126:129], v[98:113]
	v_add_f32_e32 v78, v52, v114
	v_add_f32_e32 v78, v53, v78
	v_add_f32_e32 v78, v54, v78
	v_add_f32_e32 v78, v55, v78
	v_cvt_pk_bf16_f32 v122, v50, v51
	v_cvt_pk_bf16_f32 v123, v52, v53
	ds_read_b64_tr_b16 v[50:51], v190 offset:30720
	ds_read_b64_tr_b16 v[52:53], v190 offset:31232
	s_waitcnt lgkmcnt(14)
	v_mfma_f32_32x32x16_bf16 v[82:97], v[154:157], v[126:129], v[82:97]
	v_add_f32_e32 v78, v56, v78
	v_add_f32_e32 v78, v57, v78
	v_add_f32_e32 v78, v58, v78
	v_add_f32_e32 v78, v59, v78
	v_cvt_pk_bf16_f32 v124, v54, v55
	v_cvt_pk_bf16_f32 v125, v56, v57
	ds_read_b64_tr_b16 v[54:55], v190 offset:27648
	ds_read_b64_tr_b16 v[56:57], v190 offset:28160
	s_waitcnt lgkmcnt(14)
	v_mfma_f32_32x32x16_bf16 v[98:113], v[150:153], v[118:121], v[98:113]
	v_add_f32_e32 v78, v60, v78
	v_add_f32_e32 v78, v61, v78
	v_add_f32_e32 v78, v62, v78
	v_add_f32_e32 v78, v63, v78
	v_cvt_pk_bf16_f32 v114, v58, v59
	v_cvt_pk_bf16_f32 v115, v60, v61
	ds_read_b64_tr_b16 v[58:59], v190 offset:31744
	ds_read_b64_tr_b16 v[60:61], v190 offset:32256
	v_mfma_f32_32x32x16_bf16 v[82:97], v[146:149], v[118:121], v[82:97]
	v_add_f32_e32 v78, v64, v78
	v_add_f32_e32 v78, v65, v78
	v_cvt_pk_bf16_f32 v116, v62, v63
	v_cvt_pk_bf16_f32 v117, v64, v65
	s_add_i32 s4, s11, s46
	s_mov_b32 s5, m0
	s_mov_b32 m0, s4
	s_nop 0
	global_load_lds_dwordx4 v188, s[100:101]
	s_mov_b32 m0, s5
	s_add_i32 s4, s14, s47
	s_mov_b32 s5, m0
	s_mov_b32 m0, s4
	s_nop 0
	global_load_lds_dwordx4 v186, s[100:101]
	s_mov_b32 m0, s5
	v_add_f32_e32 v190, v205, v78

.Lfast_488:
	s_add_i32 s4, s14, 0x2000
	s_cmpk_lg_i32 s14, 0x4000
	s_cselect_b32 s50, s4, 0
	v_add_u32_e32 v192, s11, v203
	ds_read_b64_tr_b16 v[150:151], v192 offset:24576
	ds_read_b64_tr_b16 v[152:153], v192 offset:25088
	s_waitcnt lgkmcnt(9)
	v_mfma_f32_32x32x16_bf16 v[66:81], v[62:65], v[142:145], v[34:49]
	v_add_f32_e32 v50, v98, v99
	v_add_f32_e32 v50, v100, v50
	v_add_f32_e32 v50, v101, v50
	v_add_f32_e32 v50, v102, v50
	v_add_f32_e32 v50, v103, v50
	v_cvt_pk_bf16_f32 v138, v98, v99
	v_cvt_pk_bf16_f32 v139, v100, v101
	ds_read_b64_tr_b16 v[146:147], v192 offset:28672
	ds_read_b64_tr_b16 v[148:149], v192 offset:29184
	v_add_f32_e32 v50, v104, v50
	v_add_f32_e32 v50, v105, v50
	v_add_f32_e32 v50, v106, v50
	v_add_f32_e32 v114, v107, v50
	s_waitcnt lgkmcnt(10)
	v_mfma_f32_32x32x16_bf16 v[50:65], v[174:177], v[142:145], v[34:49]
	v_cvt_pk_bf16_f32 v140, v102, v103
	v_cvt_pk_bf16_f32 v141, v104, v105
	ds_read_b64_tr_b16 v[98:99], v192 offset:25600
	ds_read_b64_tr_b16 v[100:101], v192 offset:26112
	s_waitcnt lgkmcnt(11)
	v_mfma_f32_32x32x16_bf16 v[66:81], v[178:181], v[134:137], v[66:81]
	v_add_f32_e32 v102, v108, v114
	v_add_f32_e32 v102, v109, v102
	v_add_f32_e32 v102, v110, v102
	v_add_f32_e32 v114, v111, v102
	v_cvt_pk_bf16_f32 v130, v106, v107
	v_cvt_pk_bf16_f32 v131, v108, v109
	ds_read_b64_tr_b16 v[102:103], v192 offset:29696
	ds_read_b64_tr_b16 v[104:105], v192 offset:30208
	s_waitcnt lgkmcnt(12)
	v_mfma_f32_32x32x16_bf16 v[50:65], v[170:173], v[134:137], v[50:65]
	v_add_f32_e32 v106, v112, v114
	v_add_f32_e32 v106, v113, v106
	v_add_f32_e32 v106, v82, v106
	v_add_f32_e32 v114, v83, v106
	v_cvt_pk_bf16_f32 v132, v110, v111
	v_cvt_pk_bf16_f32 v133, v112, v113
	ds_read_b64_tr_b16 v[106:107], v192 offset:26624
	ds_read_b64_tr_b16 v[108:109], v192 offset:27136
	s_waitcnt lgkmcnt(13)
	v_mfma_f32_32x32x16_bf16 v[66:81], v[166:169], v[126:129], v[66:81]
	v_add_f32_e32 v110, v84, v114
	v_add_f32_e32 v110, v85, v110
	v_add_f32_e32 v110, v86, v110
	v_add_f32_e32 v110, v87, v110
	v_cvt_pk_bf16_f32 v122, v82, v83
	v_cvt_pk_bf16_f32 v123, v84, v85
	ds_read_b64_tr_b16 v[82:83], v192 offset:30720
	ds_read_b64_tr_b16 v[84:85], v192 offset:31232
	s_waitcnt lgkmcnt(14)
	v_mfma_f32_32x32x16_bf16 v[50:65], v[162:165], v[126:129], v[50:65]
	v_add_f32_e32 v110, v88, v110
	v_add_f32_e32 v110, v89, v110
	v_add_f32_e32 v110, v90, v110
	v_add_f32_e32 v110, v91, v110
	v_cvt_pk_bf16_f32 v124, v86, v87
	v_cvt_pk_bf16_f32 v125, v88, v89
	ds_read_b64_tr_b16 v[86:87], v192 offset:27648
	ds_read_b64_tr_b16 v[88:89], v192 offset:28160
	s_waitcnt lgkmcnt(14)
	v_mfma_f32_32x32x16_bf16 v[66:81], v[158:161], v[118:121], v[66:81]
	v_add_f32_e32 v110, v92, v110
	v_add_f32_e32 v110, v93, v110
	v_add_f32_e32 v110, v94, v110
	v_add_f32_e32 v110, v95, v110
	v_cvt_pk_bf16_f32 v114, v90, v91
	v_cvt_pk_bf16_f32 v115, v92, v93
	ds_read_b64_tr_b16 v[90:91], v192 offset:31744
	ds_read_b64_tr_b16 v[92:93], v192 offset:32256
	v_mfma_f32_32x32x16_bf16 v[50:65], v[154:157], v[118:121], v[50:65]
	v_add_f32_e32 v110, v96, v110
	v_add_f32_e32 v110, v97, v110
	v_cvt_pk_bf16_f32 v116, v94, v95
	v_cvt_pk_bf16_f32 v117, v96, v97
	s_add_i32 s4, s14, s46
	s_mov_b32 s5, m0
	s_mov_b32 m0, s4
	s_nop 0
	global_load_lds_dwordx4 v189, s[100:101]
	s_mov_b32 m0, s5
	s_add_i32 s4, s50, s47
	s_mov_b32 s5, m0
	s_mov_b32 m0, s4
	s_nop 0
	global_load_lds_dwordx4 v187, s[100:101]
	s_mov_b32 m0, s5
	v_add_f32_e32 v205, v190, v110
.Lfast_489:
	s_waitcnt lgkmcnt(14)
	v_mfma_f32_32x32x16_bf16 v[18:33], v[138:141], v[150:153], v[18:33]
	v_exp_f32_e32 v66, v66
	v_exp_f32_e32 v67, v67
	v_exp_f32_e32 v68, v68
	v_exp_f32_e32 v69, v69
	s_waitcnt lgkmcnt(12)
	v_mfma_f32_32x32x16_bf16 v[2:17], v[138:141], v[146:149], v[2:17]
	v_exp_f32_e32 v70, v70
	v_exp_f32_e32 v71, v71
	v_exp_f32_e32 v72, v72
	v_exp_f32_e32 v73, v73
	v_add_u32_e32 v94, s50, v202
	ds_read_b128 v[174:177], v94
	ds_read_b128 v[170:173], v94 offset:512
	s_waitcnt lgkmcnt(12)
	v_mfma_f32_32x32x16_bf16 v[18:33], v[130:133], v[98:101], v[18:33]
	v_exp_f32_e32 v74, v74
	v_exp_f32_e32 v75, v75
	v_exp_f32_e32 v76, v76
	v_exp_f32_e32 v77, v77
	ds_read_b128 v[166:169], v94 offset:2048
	ds_read_b128 v[162:165], v94 offset:2560
	s_waitcnt lgkmcnt(12)
	v_mfma_f32_32x32x16_bf16 v[2:17], v[130:133], v[102:105], v[2:17]
	v_exp_f32_e32 v78, v78
	v_exp_f32_e32 v79, v79
	v_exp_f32_e32 v80, v80
	v_exp_f32_e32 v81, v81
	ds_read_b128 v[158:161], v94 offset:4096
	ds_read_b128 v[154:157], v94 offset:4608
	s_waitcnt lgkmcnt(12)
	v_mfma_f32_32x32x16_bf16 v[18:33], v[122:125], v[106:109], v[18:33]
	v_exp_f32_e32 v50, v50
	v_exp_f32_e32 v51, v51
	v_exp_f32_e32 v52, v52
	v_exp_f32_e32 v53, v53
	ds_read_b128 v[150:153], v94 offset:6144
	ds_read_b128 v[146:149], v94 offset:6656
	s_waitcnt lgkmcnt(12)
	v_mfma_f32_32x32x16_bf16 v[2:17], v[122:125], v[82:85], v[2:17]
	v_exp_f32_e32 v54, v54
	v_exp_f32_e32 v55, v55
	v_exp_f32_e32 v56, v56
	v_exp_f32_e32 v57, v57
	s_waitcnt lgkmcnt(10)
	v_mfma_f32_32x32x16_bf16 v[18:33], v[114:117], v[86:89], v[18:33]
	v_exp_f32_e32 v58, v58
	v_exp_f32_e32 v59, v59
	v_exp_f32_e32 v60, v60
	v_exp_f32_e32 v61, v61
	s_waitcnt lgkmcnt(8)
	v_mfma_f32_32x32x16_bf16 v[2:17], v[114:117], v[90:93], v[2:17]
	v_exp_f32_e32 v62, v62
	v_exp_f32_e32 v63, v63
	v_exp_f32_e32 v64, v64
	v_exp_f32_e32 v65, v65
	s_waitcnt vmcnt(2) lgkmcnt(0)
	s_barrier
.Lfast_491:
	s_add_u32 s100, s100, s42
	s_addc_u32 s101, s101, s43
	s_add_i32 s4, s50, 0x2000
	s_cmpk_lg_i32 s50, 0x4000
	s_cselect_b32 s25, s4, 0
	s_add_i32 s4, s10, 2
	s_cmp_ge_u32 s4, s19
	s_cbranch_scc1 .LBB0_500
	s_mov_b32 s10, s4
	s_mov_b32 s4, s14
	s_mov_b32 s11, s50
	s_mov_b32 s14, s25
	s_branch .Lfast_485
.LBB0_493:
	v_max_f32_e32 v34, v62, v62
	v_max_f32_e32 v62, 0, v34
	v_exp_f32_e64 v63, -v62
	v_add_f32_e32 v201, v201, v62
	v_xor_b32_e32 v34, 0x80000000, v201
	v_mov_b32_e32 v35, v34
	v_mov_b32_e32 v36, v34
	v_mov_b32_e32 v37, v34
	v_mov_b32_e32 v38, v34
	v_mov_b32_e32 v39, v34
	v_mov_b32_e32 v40, v34
	v_mov_b32_e32 v41, v34
	v_mov_b32_e32 v42, v34
	v_mov_b32_e32 v43, v34
	v_mov_b32_e32 v44, v34
	v_mov_b32_e32 v45, v34
	v_mov_b32_e32 v46, v34
	v_mov_b32_e32 v47, v34
	v_mov_b32_e32 v48, v34
	v_mov_b32_e32 v49, v34
	s_and_saveexec_b64 s[8:9], s[0:1]
	ds_write_b32 v200, v63 offset:49152
	s_or_b64 exec, exec, s[8:9]
	v_sub_f32_e32 v113, v113, v62
	v_sub_f32_e32 v112, v112, v62
	v_sub_f32_e32 v111, v111, v62
	v_sub_f32_e32 v110, v110, v62
	v_sub_f32_e32 v109, v109, v62
	v_sub_f32_e32 v108, v108, v62
	v_sub_f32_e32 v107, v107, v62
	v_sub_f32_e32 v106, v106, v62
	v_sub_f32_e32 v105, v105, v62
	v_sub_f32_e32 v104, v104, v62
	v_sub_f32_e32 v103, v103, v62
	v_sub_f32_e32 v102, v102, v62
	v_sub_f32_e32 v101, v101, v62
	v_sub_f32_e32 v100, v100, v62
	v_sub_f32_e32 v99, v99, v62
	v_sub_f32_e32 v98, v98, v62
	v_sub_f32_e32 v97, v97, v62
	v_sub_f32_e32 v96, v96, v62
	v_sub_f32_e32 v95, v95, v62
	v_sub_f32_e32 v94, v94, v62
	v_sub_f32_e32 v93, v93, v62
	v_sub_f32_e32 v92, v92, v62
	v_sub_f32_e32 v91, v91, v62
	v_sub_f32_e32 v90, v90, v62
	v_sub_f32_e32 v89, v89, v62
	v_sub_f32_e32 v88, v88, v62
	v_sub_f32_e32 v87, v87, v62
	v_sub_f32_e32 v86, v86, v62
	v_sub_f32_e32 v85, v85, v62
	v_sub_f32_e32 v84, v84, v62
	v_sub_f32_e32 v83, v83, v62
	v_sub_f32_e32 v82, v82, v62
	v_mul_f32_e32 v190, v190, v63
	s_branch .LBB0_486
